# hybrid: row-block seams everywhere except P6|P7, which re-aligns the XCD's eight row blocks (XCD-wide seam) before the 11-tile gate/up GEMM
# speedup vs baseline: 1.0036x; 1.0036x over previous
; __device__ __forceinline__ void xcd_barrier(const XcdBarrier& b) {
;     asm volatile("s_waitcnt vmcnt(0)" ::: "memory");
;     __syncthreads();
;     if (threadIdx.x == 0) {
;         unsigned* bar = b.bar;
;         __builtin_amdgcn_s_waitcnt(0);
;         unsigned nloc = b.st[0], nx = b.st[1];
;         if (nloc == 0u) { xcd_barrier_complete(bar, b.x, nloc, nx); b.st[0] = nloc; b.st[1] = nx; }
.LBB0_640:
	v_readlane_b32 s20, v255, 24
	s_add_i32 s20, s20, 5
	s_cmp_lt_i32 s20, s59
	s_cselect_b64 s[26:27], -1, 0
	s_and_b64 s[4:5], s[4:5], s[26:27]
	s_andn2_b64 vcc, exec, s[4:5]
	s_cbranch_vccnz .LBB0_694
	s_waitcnt vmcnt(0)
	s_waitcnt vmcnt(0)
	s_barrier
	s_and_saveexec_b64 s[4:5], s[74:75]
	s_cbranch_execz .LBB0_693
	s_cmp_lg_u32 s100, 0
	s_cbranch_scc1 .Lgs_known_18221
	v_readlane_b32 s22, v255, 6
	v_readlane_b32 s23, v255, 7
	s_nop 4
	global_load_dword v6, v1, s[22:23] offset:1024 sc1
	global_load_dword v7, v1, s[22:23] offset:1088 sc1
	global_load_dword v8, v1, s[22:23] offset:1152 sc1
	global_load_dword v9, v1, s[22:23] offset:1216 sc1
	global_load_dword v10, v1, s[22:23] offset:1280 sc1
	global_load_dword v11, v1, s[22:23] offset:1344 sc1
	global_load_dword v12, v1, s[22:23] offset:1408 sc1
	global_load_dword v13, v1, s[22:23] offset:1472 sc1
	s_waitcnt vmcnt(0)
	v_add_u32_e32 v14, -1, v6
	v_and_b32_e32 v14, v14, v6
	v_add_u32_e32 v15, -1, v7
	v_and_b32_e32 v15, v15, v7
	v_or_b32_e32 v14, v14, v15
	v_add_u32_e32 v15, -1, v8
	v_and_b32_e32 v15, v15, v8
	v_or_b32_e32 v14, v14, v15
	v_add_u32_e32 v15, -1, v9
	v_and_b32_e32 v15, v15, v9
	v_or_b32_e32 v14, v14, v15
	v_add_u32_e32 v15, -1, v10
	v_and_b32_e32 v15, v15, v10
	v_or_b32_e32 v14, v14, v15
	v_add_u32_e32 v15, -1, v11
	v_and_b32_e32 v15, v15, v11
	v_or_b32_e32 v14, v14, v15
	v_add_u32_e32 v15, -1, v12
	v_and_b32_e32 v15, v15, v12
	v_or_b32_e32 v14, v14, v15
	v_add_u32_e32 v15, -1, v13
	v_and_b32_e32 v15, v15, v13
	v_or_b32_e32 v14, v14, v15
	s_nop 0
	v_readfirstlane_b32 s22, v14
	s_cmp_eq_u32 s22, 0
	s_cselect_b32 s100, 1, 2
.Lgs_known_18221:
	v_readlane_b32 s22, v255, 27
	s_waitcnt vmcnt(0) expcnt(0) lgkmcnt(0)
	s_nop 0
	v_mov_b32_e32 v0, s22
	ds_read_b32 v3, v0
	v_readlane_b32 s22, v255, 28
	s_waitcnt lgkmcnt(0)
	v_cmp_ne_u32_e32 vcc, 0, v3
	v_mov_b32_e32 v0, s22
	ds_read_b32 v2, v0
	s_cbranch_vccnz .LBB0_657
	v_readlane_b32 s34, v254, 0
	v_readlane_b32 s35, v254, 1
	s_load_dwordx2 s[22:23], s[34:35], 0x4
	s_waitcnt lgkmcnt(0)
	s_mul_i32 s22, s22, s3
	s_mul_i32 s22, s22, s23
	s_mov_b32 s23, 1
	s_branch .LBB0_645

; __device__ __forceinline__ unsigned xb_add(unsigned* p, unsigned v) { return __hip_atomic_fetch_add(p, v, __ATOMIC_RELAXED, __HIP_MEMORY_SCOPE_AGENT); }
; __device__ __forceinline__ void xcd_barrier(const XcdBarrier& b) {
;     ...
;         const unsigned old = xb_add(&bar[XB_XSUB(b.x)], 1u);
;         const unsigned gen = old / nloc;
;         if (old + 1u == (gen + 1u) * nloc) {
;             __builtin_amdgcn_fence(__ATOMIC_RELEASE, "agent");
;             asm volatile("s_waitcnt vmcnt(0)" ::: "memory");
;             const unsigned og = xb_add(&bar[XB_TOP], 1u);
.LBB0_673:
	s_andn2_saveexec_b64 s[22:23], s[34:35]
	s_cbranch_execz .LBB0_693
	s_mov_b64 s[34:35], exec
	s_cmp_eq_u32 s100, 1
	s_cbranch_scc1 .LBB0_690
	buffer_wbl2 sc1
	s_waitcnt lgkmcnt(0)
	s_waitcnt vmcnt(0)
	v_mbcnt_lo_u32_b32 v0, s34, 0
	v_mbcnt_hi_u32_b32 v0, s35, v0
	v_cmp_eq_u32_e32 vcc, 0, v0
	s_and_saveexec_b64 s[36:37], vcc
	s_cbranch_execz .LBB0_676
	s_bcnt1_i32_b64 s22, s[34:35]
	v_mov_b32_e32 v3, s22
	v_readlane_b32 s22, v255, 6
	v_readlane_b32 s23, v255, 7
	s_nop 4
	global_atomic_add v3, v1, v3, s[22:23] sc0
